# gate/up epilogue: silu*u per 4 outputs as one hazard-free block (packed scale and +1, no s_nop), same per-element operation order
# speedup vs baseline: 1.0258x; 1.0069x over previous
; template <int EPI>
; DI void gemm_phase(const int wid_s, const h16* __restrict__ A, const h16* __restrict__ Bt, const int N, const int K, const EpiArgs ea) {
;     ...
;         const size_t row = (size_t)(brow + ai * HALF + wr * 64 + m * 16 + fr);
; #pragma unroll
;         for (int bj = 0; bj < 2; ++bj) {
;           const int col0 = bcol + bj * HALF + wc * 32 + 8 * fq;
;           const f32x4 v0 = acc[ai][bj][m][0], v1 = acc[ai][bj][m][1];
;           if (EPI == 0) {
;             half8 o = {(h16)v0[0], (h16)v0[1], (h16)v0[2], (h16)v0[3], (h16)v1[0], (h16)v1[1], (h16)v1[2], (h16)v1[3]};
;             *(half8*)(ea.out + row * LDH + col0) = o;
;           } else if (EPI == 1) {
;             const half8 r = *(const half8*)(ea.res + row * 1024 + col0);
;             half8 o;
; #pragma unroll
;             for (int j = 0; j < 4; ++j) { o[j] = (h16)(ALPHA_F * (float)r[j] + v0[j]); o[4 + j] = (h16)(ALPHA_F * (float)r[4 + j] + v1[j]); }
;             *(half8*)(ea.out + row * 1024 + col0) = o;
;           } else {
;             const int f0 = (bcol + bj * HALF + wc * 32) / 2 + 4 * fq;
;             half4 o;
; #pragma unroll
;             for (int j = 0; j < 4; ++j) { const float g = v0[j], u = v1[j]; o[j] = (h16)(g * __builtin_amdgcn_rcpf(1.f + __builtin_amdgcn_exp2f(g * -1.4426950408889634f)) * u); }
;             *(half4*)(ea.out + row * DFF + f0) = o;
.LBB0_144:
	v_mov_b32_e32 v212, 0xbfb8aa3b
	v_mov_b32_e32 v213, 0xbfb8aa3b
	v_mov_b32_e32 v214, 1.0
	v_mov_b32_e32 v215, 1.0
	v_readlane_b32 s11, v252, 24
	v_mbcnt_lo_u32_b32 v186, -1, 0
	v_mbcnt_hi_u32_b32 v186, -1, v186
	v_and_b32_e32 v187, 15, v186
	v_lshrrev_b32_e32 v188, 4, v186
	v_mov_b32_e32 v189, s11
	v_lshrrev_b32_e32 v190, 8, v189
	v_bfe_u32 v191, v189, 6, 2
	v_lshl_add_u32 v192, v191, 2, v188
	v_lshl_add_u32 v193, v190, 4, v187
	v_mul_u32_u24_e32 v200, 0x110, v193
	v_lshl_add_u32 v200, v191, 5, v200
	v_lshl_add_u32 v200, v188, 3, v200
	v_add_u32_e32 v200, 0x20100, v200
	v_add_u32_e32 v201, 0x2200, v200
	v_lshl_add_u32 v193, v190, 4, v192
	v_mul_u32_u24_e32 v202, 0x110, v193
	v_lshl_add_u32 v202, v187, 4, v202
	v_add_u32_e32 v202, 0x20100, v202
	v_add_u32_e32 v203, 0x2200, v202
	v_sub_u32_e32 v198, v192, v187
	v_mul_i32_i24_e32 v198, 0x1600, v198
	v_lshl_add_u32 v198, v187, 4, v198
	v_lshlrev_b32_e32 v199, 5, v191
	v_sub_u32_e32 v198, v198, v199
	v_lshlrev_b32_e32 v199, 3, v188
	v_sub_u32_e32 v198, v198, v199
	v_ashrrev_i32_e32 v199, 31, v198
	s_or_b32 s9, s18, s39
	s_ashr_i32 s9, s9, 1
	v_add_u32_e32 v146, s16, v5
	v_mov_b64_e32 v[144:145], s[28:29]
	s_movk_i32 s11, 0x1600
	v_mad_i64_i32 v[152:153], s[20:21], v146, s11, v[144:145]
	v_pk_mul_f32 v[204:205], v[130:131], v[212:213]
	v_pk_mul_f32 v[206:207], v[132:133], v[212:213]
	v_exp_f32_e32 v204, v204
	v_exp_f32_e32 v205, v205
	v_exp_f32_e32 v206, v206
	v_exp_f32_e32 v207, v207
	v_pk_add_f32 v[204:205], v[204:205], v[214:215]
	v_pk_add_f32 v[206:207], v[206:207], v[214:215]
	v_rcp_f32_e32 v204, v204
	v_rcp_f32_e32 v205, v205
	v_rcp_f32_e32 v206, v206
	v_rcp_f32_e32 v207, v207
	v_pk_mul_f32 v[204:205], v[130:131], v[204:205]
	v_pk_mul_f32 v[206:207], v[132:133], v[206:207]
	v_pk_mul_f32 v[204:205], v[126:127], v[204:205]
	v_pk_mul_f32 v[206:207], v[128:129], v[206:207]
	v_cvt_pk_f16_f32 v130, v204, v205
	v_cvt_pk_f16_f32 v131, v206, v207
	v_or_b32_e32 v126, s9, v150
	v_ashrrev_i32_e32 v127, 31, v126
	v_lshlrev_b64 v[126:127], 1, v[126:127]
	v_lshl_add_u64 v[128:129], v[152:153], 0, v[126:127]
	ds_write_b64 v200, v[130:131]
	v_pk_mul_f32 v[204:205], v[122:123], v[212:213]
	v_pk_mul_f32 v[206:207], v[124:125], v[212:213]
	v_exp_f32_e32 v204, v204
	v_exp_f32_e32 v205, v205
	v_exp_f32_e32 v206, v206
	v_exp_f32_e32 v207, v207
	v_pk_add_f32 v[204:205], v[204:205], v[214:215]
	v_pk_add_f32 v[206:207], v[206:207], v[214:215]
	v_rcp_f32_e32 v204, v204
	v_rcp_f32_e32 v205, v205
	v_rcp_f32_e32 v206, v206
	v_rcp_f32_e32 v207, v207
	v_pk_mul_f32 v[204:205], v[122:123], v[204:205]
	v_pk_mul_f32 v[206:207], v[124:125], v[206:207]
	v_pk_mul_f32 v[204:205], v[118:119], v[204:205]
	v_pk_mul_f32 v[206:207], v[120:121], v[206:207]
	v_cvt_pk_f16_f32 v118, v204, v205
	v_cvt_pk_f16_f32 v119, v206, v207
	ds_write_b64 v200, v[118:119] offset:128
	s_waitcnt lgkmcnt(0)
	s_barrier
	ds_read_b128 v[186:189], v202
	v_lshl_add_u64 v[194:195], v[198:199], 0, v[128:129]
	v_add_u32_e32 v118, 16, v146
	v_mad_i64_i32 v[118:119], s[20:21], v118, s11, v[144:145]
	v_pk_mul_f32 v[204:205], v[114:115], v[212:213]
	v_pk_mul_f32 v[206:207], v[116:117], v[212:213]
	v_exp_f32_e32 v204, v204
	v_exp_f32_e32 v205, v205
	v_exp_f32_e32 v206, v206
	v_exp_f32_e32 v207, v207
	v_pk_add_f32 v[204:205], v[204:205], v[214:215]
	v_pk_add_f32 v[206:207], v[206:207], v[214:215]
	v_rcp_f32_e32 v204, v204
	v_rcp_f32_e32 v205, v205
	v_rcp_f32_e32 v206, v206
	v_rcp_f32_e32 v207, v207
	v_pk_mul_f32 v[204:205], v[114:115], v[204:205]
	v_pk_mul_f32 v[206:207], v[116:117], v[206:207]
	v_pk_mul_f32 v[204:205], v[110:111], v[204:205]
	v_pk_mul_f32 v[206:207], v[112:113], v[206:207]
	v_cvt_pk_f16_f32 v110, v204, v205
	v_cvt_pk_f16_f32 v111, v206, v207
	v_lshl_add_u64 v[112:113], v[118:119], 0, v[126:127]
	s_waitcnt lgkmcnt(0)
	global_store_dwordx4 v[194:195], v[186:189], off
	ds_write_b64 v201, v[110:111]
	v_pk_mul_f32 v[204:205], v[106:107], v[212:213]
	v_pk_mul_f32 v[206:207], v[108:109], v[212:213]
	v_exp_f32_e32 v204, v204
	v_exp_f32_e32 v205, v205
	v_exp_f32_e32 v206, v206
	v_exp_f32_e32 v207, v207
	v_pk_add_f32 v[204:205], v[204:205], v[214:215]
	v_pk_add_f32 v[206:207], v[206:207], v[214:215]
	v_rcp_f32_e32 v204, v204
	v_rcp_f32_e32 v205, v205
	v_rcp_f32_e32 v206, v206
	v_rcp_f32_e32 v207, v207
	v_pk_mul_f32 v[204:205], v[106:107], v[204:205]
	v_pk_mul_f32 v[206:207], v[108:109], v[206:207]
	v_pk_mul_f32 v[204:205], v[102:103], v[204:205]
	v_pk_mul_f32 v[206:207], v[104:105], v[206:207]
	v_cvt_pk_f16_f32 v102, v204, v205
	v_cvt_pk_f16_f32 v103, v206, v207
	ds_write_b64 v201, v[102:103] offset:128
	s_waitcnt lgkmcnt(0)
	s_barrier
	ds_read_b128 v[190:193], v203
	v_lshl_add_u64 v[196:197], v[198:199], 0, v[112:113]
	v_add_u32_e32 v102, 32, v146
	v_mad_i64_i32 v[102:103], s[20:21], v102, s11, v[144:145]
	v_pk_mul_f32 v[204:205], v[98:99], v[212:213]
	v_pk_mul_f32 v[206:207], v[100:101], v[212:213]
	v_exp_f32_e32 v204, v204
	v_exp_f32_e32 v205, v205
	v_exp_f32_e32 v206, v206
	v_exp_f32_e32 v207, v207
	v_pk_add_f32 v[204:205], v[204:205], v[214:215]
	v_pk_add_f32 v[206:207], v[206:207], v[214:215]
	v_rcp_f32_e32 v204, v204
	v_rcp_f32_e32 v205, v205
	v_rcp_f32_e32 v206, v206
	v_rcp_f32_e32 v207, v207
	v_pk_mul_f32 v[204:205], v[98:99], v[204:205]
	v_pk_mul_f32 v[206:207], v[100:101], v[206:207]
	v_pk_mul_f32 v[204:205], v[94:95], v[204:205]
	v_pk_mul_f32 v[206:207], v[96:97], v[206:207]
	v_cvt_pk_f16_f32 v94, v204, v205
	v_cvt_pk_f16_f32 v95, v206, v207
	v_lshl_add_u64 v[96:97], v[102:103], 0, v[126:127]
	s_waitcnt lgkmcnt(0)
	global_store_dwordx4 v[196:197], v[190:193], off
	ds_write_b64 v200, v[94:95]
	v_pk_mul_f32 v[204:205], v[90:91], v[212:213]
	v_pk_mul_f32 v[206:207], v[92:93], v[212:213]
	v_exp_f32_e32 v204, v204
	v_exp_f32_e32 v205, v205
	v_exp_f32_e32 v206, v206
	v_exp_f32_e32 v207, v207
	v_pk_add_f32 v[204:205], v[204:205], v[214:215]
	v_pk_add_f32 v[206:207], v[206:207], v[214:215]
	v_rcp_f32_e32 v204, v204
	v_rcp_f32_e32 v205, v205
	v_rcp_f32_e32 v206, v206
	v_rcp_f32_e32 v207, v207
	v_pk_mul_f32 v[204:205], v[90:91], v[204:205]
	v_pk_mul_f32 v[206:207], v[92:93], v[206:207]
	v_pk_mul_f32 v[204:205], v[86:87], v[204:205]
	v_pk_mul_f32 v[206:207], v[88:89], v[206:207]
	v_cvt_pk_f16_f32 v86, v204, v205
	v_cvt_pk_f16_f32 v87, v206, v207
	ds_write_b64 v200, v[86:87] offset:128
	s_waitcnt lgkmcnt(0)
	s_barrier
; template <int EPI>
; DI void gemm_phase(const int wid_s, const h16* __restrict__ A, const h16* __restrict__ Bt, const int N, const int K, const EpiArgs ea) {
;     ...
;             const int f0 = (bcol + bj * HALF + wc * 32) / 2 + 4 * fq;
;             half4 o;
; #pragma unroll
;             for (int j = 0; j < 4; ++j) { const float g = v0[j], u = v1[j]; o[j] = (h16)(g * __builtin_amdgcn_rcpf(1.f + __builtin_amdgcn_exp2f(g * -1.4426950408889634f)) * u); }
;             *(half4*)(ea.out + row * DFF + f0) = o;
	ds_read_b128 v[186:189], v202
	v_lshl_add_u64 v[194:195], v[198:199], 0, v[96:97]
	v_add_u32_e32 v86, 48, v146
	v_mad_i64_i32 v[86:87], s[20:21], v86, s11, v[144:145]
	v_pk_mul_f32 v[204:205], v[82:83], v[212:213]
	v_pk_mul_f32 v[206:207], v[84:85], v[212:213]
	v_exp_f32_e32 v204, v204
	v_exp_f32_e32 v205, v205
	v_exp_f32_e32 v206, v206
	v_exp_f32_e32 v207, v207
	v_pk_add_f32 v[204:205], v[204:205], v[214:215]
	v_pk_add_f32 v[206:207], v[206:207], v[214:215]
	v_rcp_f32_e32 v204, v204
	v_rcp_f32_e32 v205, v205
	v_rcp_f32_e32 v206, v206
	v_rcp_f32_e32 v207, v207
	v_pk_mul_f32 v[204:205], v[82:83], v[204:205]
	v_pk_mul_f32 v[206:207], v[84:85], v[206:207]
	v_pk_mul_f32 v[204:205], v[78:79], v[204:205]
	v_pk_mul_f32 v[206:207], v[80:81], v[206:207]
	v_cvt_pk_f16_f32 v78, v204, v205
	v_cvt_pk_f16_f32 v79, v206, v207
	v_lshl_add_u64 v[80:81], v[86:87], 0, v[126:127]
	s_waitcnt lgkmcnt(0)
	global_store_dwordx4 v[194:195], v[186:189], off
	ds_write_b64 v201, v[78:79]
	v_pk_mul_f32 v[204:205], v[74:75], v[212:213]
	v_pk_mul_f32 v[206:207], v[76:77], v[212:213]
	v_exp_f32_e32 v204, v204
	v_exp_f32_e32 v205, v205
	v_exp_f32_e32 v206, v206
	v_exp_f32_e32 v207, v207
	v_pk_add_f32 v[204:205], v[204:205], v[214:215]
	v_pk_add_f32 v[206:207], v[206:207], v[214:215]
	v_rcp_f32_e32 v204, v204
	v_rcp_f32_e32 v205, v205
	v_rcp_f32_e32 v206, v206
	v_rcp_f32_e32 v207, v207
	v_pk_mul_f32 v[204:205], v[74:75], v[204:205]
	v_pk_mul_f32 v[206:207], v[76:77], v[206:207]
	v_pk_mul_f32 v[204:205], v[70:71], v[204:205]
	v_pk_mul_f32 v[206:207], v[72:73], v[206:207]
	v_cvt_pk_f16_f32 v70, v204, v205
	v_cvt_pk_f16_f32 v71, v206, v207
	ds_write_b64 v201, v[70:71] offset:128
	s_waitcnt lgkmcnt(0)
	s_barrier
	ds_read_b128 v[190:193], v203
	v_lshl_add_u64 v[196:197], v[198:199], 0, v[80:81]
	v_add_u32_e32 v70, 0x80, v146
	v_mad_i64_i32 v[70:71], s[20:21], v70, s11, v[144:145]
	v_pk_mul_f32 v[204:205], v[66:67], v[212:213]
	v_pk_mul_f32 v[206:207], v[68:69], v[212:213]
	v_exp_f32_e32 v204, v204
	v_exp_f32_e32 v205, v205
	v_exp_f32_e32 v206, v206
	v_exp_f32_e32 v207, v207
	v_pk_add_f32 v[204:205], v[204:205], v[214:215]
	v_pk_add_f32 v[206:207], v[206:207], v[214:215]
	v_rcp_f32_e32 v204, v204
	v_rcp_f32_e32 v205, v205
	v_rcp_f32_e32 v206, v206
	v_rcp_f32_e32 v207, v207
	v_pk_mul_f32 v[204:205], v[66:67], v[204:205]
	v_pk_mul_f32 v[206:207], v[68:69], v[206:207]
	v_pk_mul_f32 v[204:205], v[62:63], v[204:205]
	v_pk_mul_f32 v[206:207], v[64:65], v[206:207]
	v_cvt_pk_f16_f32 v62, v204, v205
	v_cvt_pk_f16_f32 v63, v206, v207
	v_lshl_add_u64 v[64:65], v[70:71], 0, v[126:127]
	s_waitcnt lgkmcnt(0)
	global_store_dwordx4 v[196:197], v[190:193], off
	ds_write_b64 v200, v[62:63]
	v_pk_mul_f32 v[204:205], v[58:59], v[212:213]
	v_pk_mul_f32 v[206:207], v[60:61], v[212:213]
	v_exp_f32_e32 v204, v204
	v_exp_f32_e32 v205, v205
	v_exp_f32_e32 v206, v206
	v_exp_f32_e32 v207, v207
	v_pk_add_f32 v[204:205], v[204:205], v[214:215]
	v_pk_add_f32 v[206:207], v[206:207], v[214:215]
	v_rcp_f32_e32 v204, v204
	v_rcp_f32_e32 v205, v205
	v_rcp_f32_e32 v206, v206
	v_rcp_f32_e32 v207, v207
	v_pk_mul_f32 v[204:205], v[58:59], v[204:205]
	v_pk_mul_f32 v[206:207], v[60:61], v[206:207]
	v_pk_mul_f32 v[204:205], v[54:55], v[204:205]
	v_pk_mul_f32 v[206:207], v[56:57], v[206:207]
	v_cvt_pk_f16_f32 v54, v204, v205
	v_cvt_pk_f16_f32 v55, v206, v207
	ds_write_b64 v200, v[54:55] offset:128
	s_waitcnt lgkmcnt(0)
	s_barrier
	ds_read_b128 v[186:189], v202
	v_lshl_add_u64 v[194:195], v[198:199], 0, v[64:65]
	v_add_u32_e32 v54, 0x90, v146
	v_mad_i64_i32 v[54:55], s[20:21], v54, s11, v[144:145]
	v_pk_mul_f32 v[204:205], v[50:51], v[212:213]
	v_pk_mul_f32 v[206:207], v[52:53], v[212:213]
	v_exp_f32_e32 v204, v204
	v_exp_f32_e32 v205, v205
	v_exp_f32_e32 v206, v206
	v_exp_f32_e32 v207, v207
	v_pk_add_f32 v[204:205], v[204:205], v[214:215]
	v_pk_add_f32 v[206:207], v[206:207], v[214:215]
	v_rcp_f32_e32 v204, v204
	v_rcp_f32_e32 v205, v205
	v_rcp_f32_e32 v206, v206
	v_rcp_f32_e32 v207, v207
	v_pk_mul_f32 v[204:205], v[50:51], v[204:205]
	v_pk_mul_f32 v[206:207], v[52:53], v[206:207]
	v_pk_mul_f32 v[204:205], v[46:47], v[204:205]
	v_pk_mul_f32 v[206:207], v[48:49], v[206:207]
	v_cvt_pk_f16_f32 v46, v204, v205
	v_cvt_pk_f16_f32 v47, v206, v207
	v_lshl_add_u64 v[48:49], v[54:55], 0, v[126:127]
	s_waitcnt lgkmcnt(0)
	global_store_dwordx4 v[194:195], v[186:189], off
	ds_write_b64 v201, v[46:47]
	v_pk_mul_f32 v[204:205], v[42:43], v[212:213]
	v_pk_mul_f32 v[206:207], v[44:45], v[212:213]
	v_exp_f32_e32 v204, v204
	v_exp_f32_e32 v205, v205
	v_exp_f32_e32 v206, v206
	v_exp_f32_e32 v207, v207
	v_pk_add_f32 v[204:205], v[204:205], v[214:215]
	v_pk_add_f32 v[206:207], v[206:207], v[214:215]
	v_rcp_f32_e32 v204, v204
	v_rcp_f32_e32 v205, v205
	v_rcp_f32_e32 v206, v206
	v_rcp_f32_e32 v207, v207
	v_pk_mul_f32 v[204:205], v[42:43], v[204:205]
	v_pk_mul_f32 v[206:207], v[44:45], v[206:207]
	v_pk_mul_f32 v[204:205], v[38:39], v[204:205]
	v_pk_mul_f32 v[206:207], v[40:41], v[206:207]
	v_cvt_pk_f16_f32 v38, v204, v205
	v_cvt_pk_f16_f32 v39, v206, v207
	ds_write_b64 v201, v[38:39] offset:128
	s_waitcnt lgkmcnt(0)
	s_barrier
; #define SCHED __builtin_amdgcn_sched_barrier(0)
; template <int EPI>
; DI void gemm_phase(const int wid_s, const h16* __restrict__ A, const h16* __restrict__ Bt, const int N, const int K, const EpiArgs ea) {
;     ...
;             const int f0 = (bcol + bj * HALF + wc * 32) / 2 + 4 * fq;
;             half4 o;
; #pragma unroll
;             for (int j = 0; j < 4; ++j) { const float g = v0[j], u = v1[j]; o[j] = (h16)(g * __builtin_amdgcn_rcpf(1.f + __builtin_amdgcn_exp2f(g * -1.4426950408889634f)) * u); }
;             *(half4*)(ea.out + row * DFF + f0) = o;
;           }
;         }
;         SCHED;
;       }
;     if (!has_next) break;
	ds_read_b128 v[190:193], v203
	v_lshl_add_u64 v[196:197], v[198:199], 0, v[48:49]
	v_add_u32_e32 v38, 0xa0, v146
	v_mad_i64_i32 v[38:39], s[20:21], v38, s11, v[144:145]
	v_pk_mul_f32 v[204:205], v[34:35], v[212:213]
	v_pk_mul_f32 v[206:207], v[36:37], v[212:213]
	v_exp_f32_e32 v204, v204
	v_exp_f32_e32 v205, v205
	v_exp_f32_e32 v206, v206
	v_exp_f32_e32 v207, v207
	v_pk_add_f32 v[204:205], v[204:205], v[214:215]
	v_pk_add_f32 v[206:207], v[206:207], v[214:215]
	v_rcp_f32_e32 v204, v204
	v_rcp_f32_e32 v205, v205
	v_rcp_f32_e32 v206, v206
	v_rcp_f32_e32 v207, v207
	v_pk_mul_f32 v[204:205], v[34:35], v[204:205]
	v_pk_mul_f32 v[206:207], v[36:37], v[206:207]
	v_pk_mul_f32 v[204:205], v[30:31], v[204:205]
	v_pk_mul_f32 v[206:207], v[32:33], v[206:207]
	v_cvt_pk_f16_f32 v30, v204, v205
	v_cvt_pk_f16_f32 v31, v206, v207
	v_lshl_add_u64 v[32:33], v[38:39], 0, v[126:127]
	s_waitcnt lgkmcnt(0)
	global_store_dwordx4 v[196:197], v[190:193], off
	ds_write_b64 v200, v[30:31]
	v_pk_mul_f32 v[204:205], v[26:27], v[212:213]
	v_pk_mul_f32 v[206:207], v[28:29], v[212:213]
	v_exp_f32_e32 v204, v204
	v_exp_f32_e32 v205, v205
	v_exp_f32_e32 v206, v206
	v_exp_f32_e32 v207, v207
	v_pk_add_f32 v[204:205], v[204:205], v[214:215]
	v_pk_add_f32 v[206:207], v[206:207], v[214:215]
	v_rcp_f32_e32 v204, v204
	v_rcp_f32_e32 v205, v205
	v_rcp_f32_e32 v206, v206
	v_rcp_f32_e32 v207, v207
	v_pk_mul_f32 v[204:205], v[26:27], v[204:205]
	v_pk_mul_f32 v[206:207], v[28:29], v[206:207]
	v_pk_mul_f32 v[204:205], v[22:23], v[204:205]
	v_pk_mul_f32 v[206:207], v[24:25], v[206:207]
	v_cvt_pk_f16_f32 v22, v204, v205
	v_cvt_pk_f16_f32 v23, v206, v207
	ds_write_b64 v200, v[22:23] offset:128
	s_waitcnt lgkmcnt(0)
	s_barrier
	ds_read_b128 v[186:189], v202
	v_lshl_add_u64 v[194:195], v[198:199], 0, v[32:33]
	v_add_u32_e32 v22, 0xb0, v146
	v_mad_i64_i32 v[22:23], s[20:21], v22, s11, v[144:145]
	v_pk_mul_f32 v[204:205], v[18:19], v[212:213]
	v_pk_mul_f32 v[206:207], v[20:21], v[212:213]
	v_exp_f32_e32 v204, v204
	v_exp_f32_e32 v205, v205
	v_exp_f32_e32 v206, v206
	v_exp_f32_e32 v207, v207
	v_pk_add_f32 v[204:205], v[204:205], v[214:215]
	v_pk_add_f32 v[206:207], v[206:207], v[214:215]
	v_rcp_f32_e32 v204, v204
	v_rcp_f32_e32 v205, v205
	v_rcp_f32_e32 v206, v206
	v_rcp_f32_e32 v207, v207
	v_pk_mul_f32 v[204:205], v[18:19], v[204:205]
	v_pk_mul_f32 v[206:207], v[20:21], v[206:207]
	v_pk_mul_f32 v[204:205], v[14:15], v[204:205]
	v_pk_mul_f32 v[206:207], v[16:17], v[206:207]
	v_cvt_pk_f16_f32 v14, v204, v205
	v_cvt_pk_f16_f32 v15, v206, v207
	v_lshl_add_u64 v[16:17], v[22:23], 0, v[126:127]
	s_waitcnt lgkmcnt(0)
	global_store_dwordx4 v[194:195], v[186:189], off
	ds_write_b64 v201, v[14:15]
	v_pk_mul_f32 v[204:205], v[10:11], v[212:213]
	v_pk_mul_f32 v[206:207], v[12:13], v[212:213]
	v_exp_f32_e32 v204, v204
	v_exp_f32_e32 v205, v205
	v_exp_f32_e32 v206, v206
	v_exp_f32_e32 v207, v207
	v_pk_add_f32 v[204:205], v[204:205], v[214:215]
	v_pk_add_f32 v[206:207], v[206:207], v[214:215]
	v_rcp_f32_e32 v204, v204
	v_rcp_f32_e32 v205, v205
	v_rcp_f32_e32 v206, v206
	v_rcp_f32_e32 v207, v207
	v_pk_mul_f32 v[204:205], v[10:11], v[204:205]
	v_pk_mul_f32 v[206:207], v[12:13], v[206:207]
	v_pk_mul_f32 v[204:205], v[6:7], v[204:205]
	v_pk_mul_f32 v[206:207], v[8:9], v[206:207]
	v_cvt_pk_f16_f32 v6, v204, v205
	v_cvt_pk_f16_f32 v7, v206, v207
	ds_write_b64 v201, v[6:7] offset:128
	s_waitcnt lgkmcnt(0)
	s_barrier
	ds_read_b128 v[190:193], v203
	v_lshl_add_u64 v[196:197], v[198:199], 0, v[16:17]
	s_waitcnt lgkmcnt(0)
	global_store_dwordx4 v[196:197], v[190:193], off
	v_readlane_b32 s48, v249, 37
	v_readlane_b32 s50, v249, 41
	s_andn2_b64 vcc, exec, s[6:7]
	s_mov_b64 s[6:7], -1
	s_movk_i32 s26, 0x1fff
	v_readlane_b32 s49, v249, 38
	v_readlane_b32 s51, v249, 42
	s_cbranch_vccnz .LBB0_137
	s_andn2_b64 vcc, exec, s[0:1]
	s_cbranch_vccnz .LBB0_136
	s_barrier
	s_branch .LBB0_136
